# attention tile loop unrolled x2: K-fragment LDS addresses precomputed once per unit (buffer parity via immediate offset), P register ping-pong removes 8 copies per tile, l update fused into one fma
# speedup vs baseline: 1.0538x; 1.0034x over previous
; DI void attn_stage(const bf16_t* kbase, const bf16_t* vbase, unsigned koff, unsigned voff, LAS unsigned char* ldsbuf, int wid) {
; #pragma unroll
;     for (int i = 0; i < 2; ++i) {
;         const char* src = (const char*)kbase + (size_t)(i * 128) * 2;
;         __builtin_amdgcn_global_load_lds((const unsigned*)(src + koff), (LAS unsigned*)(ldsbuf + (wid + 8 * i) * 1024), 16, 0, 0);
;     }
; #pragma unroll
;     for (int i = 0; i < 2; ++i) {
;         const char* src = (const char*)vbase + (size_t)(16 * i * 2048) * 2;
; DI void phase_attn(int wid0, const Params& p, int L, unsigned char* lds, bool dry) {
;     ...
;         { const int row = 4 * wid + (lane >> 4), gsrc = (lane & 15) ^ (row & 7); koff = (unsigned)(row * 2048 + 8 * gsrc) * 2u;
;           const int w5 = (lane & 31) >> 2, kl = (w5 & 3) + 8 * (w5 >> 2) + 4 * (wid >> 2), col = ((2 * wid + (lane >> 5)) & 7) * 32 + (lane & 3) * 8; voff = (unsigned)(kl * 2048 + col) * 2u; }
;         if (G == 256) {
;             if (ui < 8) { const int bh = 8 * ui + (blk & 7), j = blk >> 3; qb = (ui & 1) ? j : 31 - j; b = bh >> 3; hh = bh & 7; }
;             else if (ui == 8 && blk < 8) { meta = true; hh = blk; b = 0; qb = 0; }
;             else break;
;         } else {
;             const int u = blk + ui * G;
;             if (u < 2048) { const int bh = u & 63; qb = 31 - (u >> 6); b = bh >> 3; hh = bh & 7; }
;             else if (u < 2056) { meta = true; hh = u - 2048; b = 0; qb = 0; }
;             else break;
;         }
;         const int qrow0 = meta ? MREG : b * 4096 + 128 * qb, qpos0 = meta ? 0 : 16 + 128 * qb, ntiles = meta ? 1 : 1 + 4 * (qb + 1);
;         if (tid < 130) tab[tid] = (tid < 129) ? biasT[hh * 129 + tid] : -__builtin_inff();
;         int myrow = qrow0 + 32 * rg + r32; if (meta && myrow > MREG + 63) myrow = MREG + 63;
;         const bf16_t* qp = qbuf + (size_t)myrow * 2048 + hh * 256 + psub * 128 + hi * 8;
;         unsigned char* qlds = lds + wid * 8192 + lane * 16;
; #pragma unroll
;         for (int d0 = 0; d0 < 8; ++d0) *(bf16x8*)(qlds + d0 * 1024) = *(const bf16x8*)(qp + d0 * 16);
;         const int wq0 = qpos0 + 32 * rg, qpos = wq0 + r32;
;         const float bfar = biasT[hh * 129 + 128];
;         const bf16_t* kh_ = kbuf + hh * 256; const bf16_t* vh_ = vbuf + hh * 256;
;         attn_stage(kh_ + (size_t)MREG * 2048, vh_ + (size_t)MREG * 2048, koff, voff, ldsl + 65536, wid);
.LBB0_97:
	s_or_b64 exec, exec, s[10:11]
	s_lshl_b32 s40, s73, 12
	s_lshl_b32 s10, s75, 7
	s_add_i32 s9, s40, s10
	s_and_b64 s[6:7], s[76:77], exec
	s_cselect_b32 s71, 0x8000, s9
	s_lshl_b32 s6, s75, 2
	s_add_i32 s9, s6, 5
	s_and_b64 s[6:7], s[76:77], exec
	v_ashrrev_i32_e32 v0, 4, v4
	v_readlane_b32 s7, v245, 61
	v_and_b32_e32 v2, 15, v4
	v_lshrrev_b32_e32 v3, 1, v4
	v_add_u32_e32 v0, s7, v0
	v_bitop3_b32 v2, v0, v2, 15 bitop3:0x6c
	v_lshlrev_b32_e32 v0, 12, v0
	v_lshl_or_b32 v0, v2, 4, v0
	v_lshrrev_b32_e32 v2, 2, v4
	v_and_b32_e32 v3, 8, v3
	v_readlane_b32 s7, v245, 63
	v_and_or_b32 v2, v2, 3, v3
	v_lshlrev_b32_e32 v8, 3, v4
	v_add_u32_e32 v3, s7, v4
	v_readlane_b32 s7, v244, 1
	v_and_b32_e32 v7, 31, v4
	v_and_b32_e32 v3, 0xe0, v3
	v_and_b32_e32 v5, 24, v8
	v_lshl_add_u32 v2, v2, 11, s7
	v_or3_b32 v2, v2, v3, v5
	v_or_b32_e32 v3, s41, v7
	v_or_b32_e32 v3, s71, v3
	v_min_i32_e32 v9, 0x803f, v3
	v_cndmask_b32_e64 v10, v3, v9, s[76:77]
	s_cselect_b32 s6, 1, s9
	v_ashrrev_i32_e32 v11, 31, v10
	s_lshl_b32 s12, s49, 8
	v_lshlrev_b64 v[10:11], 12, v[10:11]
	s_ashr_i32 s13, s12, 31
	v_ashrrev_i32_e32 v6, 5, v4
	v_lshl_add_u64 v[10:11], s[0:1], 0, v[10:11]
	s_lshl_b64 s[78:79], s[12:13], 1
	v_readlane_b32 s12, v244, 5
	v_lshl_add_u64 v[10:11], v[10:11], 0, s[78:79]
	v_readlane_b32 s13, v244, 6
	v_lshlrev_b32_e32 v12, 3, v6
	v_ashrrev_i32_e32 v13, 31, v12
	v_lshl_add_u64 v[10:11], s[12:13], 1, v[10:11]
	v_lshl_add_u64 v[14:15], v[12:13], 1, v[10:11]
	global_load_dwordx4 v[248:251], v[14:15], off
	s_ashr_i32 s9, s8, 31
	s_lshl_b64 s[8:9], s[8:9], 2
	v_readlane_b32 s12, v245, 40
	v_lshlrev_b32_e32 v9, 4, v4
	v_readlane_b32 s7, v244, 7
	v_readlane_b32 s13, v245, 41
	s_add_u32 s8, s12, s8
	s_addc_u32 s9, s13, s9
	global_load_dword v176, v1, s[8:9] offset:512
	s_add_u32 s12, s28, s78
	s_addc_u32 s13, s29, s79
	s_mov_b64 s[84:85], s[12:13]
	v_readlane_b32 s8, v245, 38
	v_readlane_b32 s9, v245, 39
	s_add_u32 s8, s8, s78
	v_readlane_b32 s7, v244, 9
	s_addc_u32 s9, s9, s79
	s_mov_b64 s[86:87], s[8:9]
	v_lshl_add_u64 v[178:179], s[12:13], 0, v[0:1]
	v_mov_b32_e32 v131, v0
	s_mov_b64 s[14:15], 0x8000000
	s_add_i32 s7, s7, 0
	v_lshlrev_b32_e32 v2, 1, v2
	s_add_i32 m0, s7, 0x10000
	s_mov_b64 s[12:13], 0x8000100
	v_mov_b32_e32 v3, v1
	v_lshl_add_u64 v[180:181], s[8:9], 0, v[2:3]
	v_mov_b32_e32 v208, v2
	v_lshl_add_u64 v[2:3], v[180:181], 0, s[14:15]
	s_mov_b64 s[8:9], 0x8010000
	global_load_dwordx4 v[252:255], v[14:15], off offset:32
	global_load_dwordx4 v[200:203], v[14:15], off offset:64
	global_load_dwordx4 v[204:207], v[14:15], off offset:96
	global_load_dwordx4 v[164:167], v[14:15], off offset:128
	global_load_dwordx4 v[168:171], v[14:15], off offset:160
	global_load_dwordx4 v[172:175], v[14:15], off offset:192
	global_load_dwordx4 v[232:235], v[14:15], off offset:224
	v_lshl_add_u64 v[10:11], v[178:179], 0, s[14:15]
	global_load_lds_dwordx4 v[10:11], off
	v_lshl_add_u64 v[10:11], v[178:179], 0, s[12:13]
	s_add_i32 m0, s7, 0x12000
	s_nop 0
	global_load_lds_dwordx4 v[10:11], off
	s_add_i32 m0, s7, 0x14000
	s_nop 0
	global_load_lds_dwordx4 v[2:3], off
	v_lshl_add_u64 v[2:3], v[180:181], 0, s[8:9]
	s_add_i32 m0, s7, 0x16000
	s_mov_b32 s7, 0
	global_load_lds_dwordx4 v[2:3], off
	s_cmp_lt_i32 s6, 1
	s_cbranch_scc1 .LBB0_114
; DI void phase_attn(int wid0, const Params& p, int L, unsigned char* lds, bool dry) {
;     ...
; #pragma unroll
;             for (int r = 0; r < 16; ++r) o[d][r] = 0.f;
;         float m_reg = -1e30f, l_reg = 0.f;
;         for (int t = 0; t < ntiles; ++t) {
;             asm volatile("s_waitcnt vmcnt(0) lgkmcnt(0)" ::: "memory"); __builtin_amdgcn_s_barrier(); asm volatile("" ::: "memory");
;             if (t + 1 < ntiles) attn_stage(kh_ + (size_t)(b * 4096 + 32 * t) * 2048, vh_ + (size_t)(b * 4096 + 32 * t) * 2048, koff, voff, ldsl + 65536 + ((t + 1) & 1) * 32768, wid);
;             const int kpos0 = (t == 0) ? 0 : 16 + 32 * (t - 1);
;             if (kpos0 <= wq0 + 31) {
;                 const unsigned char* Ks = lds + 65536 + (t & 1) * 32768 + psub * 8192;
;                 f32x16 p0, p0b;
; #pragma unroll
;                 for (int r = 0; r < 16; ++r) { p0[r] = 0.f; p0b[r] = 0.f; }
;                 int swz = (r32 & 6) << 4, kro = r32 * 256 + ((hi ^ (r32 & 1)) << 4); asm volatile("" : "+v"(swz), "+v"(kro));
; #pragma unroll
;                 for (int d0 = 0; d0 < 8; d0 += 2) {
;                     const bf16x8 b0 = *(const bf16x8*)(Ks + kro + ((d0 * 32) ^ swz));
	s_or_b32 s10, s10, 16
	v_lshlrev_b32_e32 v0, 8, v7
	v_bitop3_b32 v2, v6, v4, 1 bitop3:0x78
	s_and_b64 s[8:9], s[76:77], exec
	v_lshl_add_u32 v193, v2, 4, v0
	v_lshlrev_b32_e32 v2, 1, v4
	s_cselect_b32 s39, 0, s10
	v_and_b32_e32 v0, 0xc0, v9
	v_and_b32_e32 v2, 32, v2
	v_readlane_b32 s48, v244, 17
	s_or_b32 s8, s39, s41
	v_and_b32_e32 v3, 0x100, v8
	v_add3_u32 v0, s48, v0, v2
	v_mov_b32_e32 v14, v1
	v_mov_b32_e32 v15, v1
	s_add_i32 s38, s8, 31
	v_and_b32_e32 v192, 0xe0, v9
	v_lshlrev_b32_e32 v194, 2, v6
	v_add_u32_e32 v195, s8, v7
	v_cmp_gt_u32_e64 s[8:9], 32, v4
	v_lshl_add_u32 v196, v7, 2, s2
	v_lshlrev_b32_e32 v16, 4, v6
	v_cmp_gt_i32_e64 s[10:11], 4, v6
	v_cmp_gt_i32_e64 s[18:19], 2, v6
	v_cmp_gt_i32_e64 s[20:21], 0, v6
	v_cmp_gt_i32_e64 s[22:23], -2, v6
	v_add3_u32 v212, v0, v3, v5
	v_mov_b32_e32 v0, v1
	v_mov_b32_e32 v2, v1
	v_mov_b32_e32 v3, v1
	v_mov_b32_e32 v4, v1
	v_mov_b32_e32 v5, v1
	v_mov_b32_e32 v6, v1
	v_mov_b32_e32 v7, v1
	v_mov_b32_e32 v8, v1
	v_mov_b32_e32 v9, v1
	v_mov_b32_e32 v10, v1
	v_mov_b32_e32 v11, v1
	v_mov_b32_e32 v12, v1
	v_mov_b32_e32 v13, v1
	v_mov_b64_e32 v[128:129], v[14:15]
	v_mov_b64_e32 v[112:113], v[14:15]
	v_mov_b64_e32 v[96:97], v[14:15]
	v_mov_b64_e32 v[80:81], v[14:15]
	v_mov_b64_e32 v[64:65], v[14:15]
	v_mov_b64_e32 v[48:49], v[14:15]
	v_mov_b64_e32 v[32:33], v[14:15]
	v_or_b32_e32 v197, 1, v194
	v_or_b32_e32 v198, 2, v194
	v_or_b32_e32 v199, 3, v194
	v_readlane_b32 s48, v244, 19
	v_add_u32_e32 v214, s2, v16
	v_mov_b64_e32 v[126:127], v[12:13]
	v_mov_b64_e32 v[124:125], v[10:11]
	v_mov_b64_e32 v[122:123], v[8:9]
	v_mov_b64_e32 v[120:121], v[6:7]
	v_mov_b64_e32 v[118:119], v[4:5]
	v_mov_b64_e32 v[116:117], v[2:3]
	v_mov_b64_e32 v[114:115], v[0:1]
	v_mov_b64_e32 v[110:111], v[12:13]
	v_mov_b64_e32 v[108:109], v[10:11]
	v_mov_b64_e32 v[106:107], v[8:9]
	v_mov_b64_e32 v[104:105], v[6:7]
	v_mov_b64_e32 v[102:103], v[4:5]
	v_mov_b64_e32 v[100:101], v[2:3]
	v_mov_b64_e32 v[98:99], v[0:1]
	v_mov_b64_e32 v[94:95], v[12:13]
	v_mov_b64_e32 v[92:93], v[10:11]
	v_mov_b64_e32 v[90:91], v[8:9]
	v_mov_b64_e32 v[88:89], v[6:7]
	v_mov_b64_e32 v[86:87], v[4:5]
	v_mov_b64_e32 v[84:85], v[2:3]
	v_mov_b64_e32 v[82:83], v[0:1]
	v_mov_b64_e32 v[78:79], v[12:13]
	v_mov_b64_e32 v[76:77], v[10:11]
	v_mov_b64_e32 v[74:75], v[8:9]
	v_mov_b64_e32 v[72:73], v[6:7]
	v_mov_b64_e32 v[70:71], v[4:5]
	v_mov_b64_e32 v[68:69], v[2:3]
	v_mov_b64_e32 v[66:67], v[0:1]
	v_mov_b64_e32 v[62:63], v[12:13]
	v_mov_b64_e32 v[60:61], v[10:11]
	v_mov_b64_e32 v[58:59], v[8:9]
	v_mov_b64_e32 v[56:57], v[6:7]
	v_mov_b64_e32 v[54:55], v[4:5]
	v_mov_b64_e32 v[52:53], v[2:3]
	v_mov_b64_e32 v[50:51], v[0:1]
	v_mov_b64_e32 v[46:47], v[12:13]
	v_mov_b64_e32 v[44:45], v[10:11]
	v_mov_b64_e32 v[42:43], v[8:9]
	v_mov_b64_e32 v[40:41], v[6:7]
	v_mov_b64_e32 v[38:39], v[4:5]
	v_mov_b64_e32 v[36:37], v[2:3]
	v_mov_b64_e32 v[34:35], v[0:1]
	v_mov_b64_e32 v[30:31], v[12:13]
	v_mov_b64_e32 v[28:29], v[10:11]
	v_mov_b64_e32 v[26:27], v[8:9]
	v_mov_b64_e32 v[24:25], v[6:7]
	v_mov_b64_e32 v[22:23], v[4:5]
	v_mov_b64_e32 v[20:21], v[2:3]
	v_mov_b64_e32 v[18:19], v[0:1]
	v_mov_b64_e32 v[16:17], v[14:15]
	v_cmp_gt_i32_e64 s[12:13], 16, v197
	v_cmp_gt_i32_e64 s[14:15], 16, v198
	v_cmp_gt_i32_e64 s[16:17], 16, v199
	s_waitcnt vmcnt(11)
	v_mov_b32_e32 v182, v176
	v_mov_b32_e32 v183, v176
	s_add_i32 s39, s48, s39
	v_mov_b32_e32 v130, 0
	v_mov_b32_e32 v213, 0xf149f2ca
	s_mov_b32 s66, 0
	s_mov_b32 s100, 0
	s_mov_b32 s101, 0
	v_mov_b32_e32 v132, 0
	v_mov_b32_e32 v133, 0
	v_mov_b32_e32 v134, 0
	v_mov_b32_e32 v135, 0
	v_mov_b32_e32 v136, 0
	v_mov_b32_e32 v137, 0
	v_mov_b32_e32 v138, 0
	v_mov_b32_e32 v139, 0
	v_add_u32_e32 v226, s5, v193
	v_add_u32_e32 v188, v226, v192
	v_xad_u32 v177, v192, 32, v226
	v_xad_u32 v209, v192, 64, v226
	s_movk_i32 s80, 0x60
	v_xad_u32 v210, v192, s80, v226
	s_movk_i32 s80, 0x80
	v_xad_u32 v211, v192, s80, v226
	s_movk_i32 s80, 0xa0
	v_xad_u32 v215, v192, s80, v226
	s_movk_i32 s80, 0xc0
	v_xad_u32 v224, v192, s80, v226
	s_movk_i32 s80, 0xe0
	v_xad_u32 v225, v192, s80, v226
	v_mov_b64_e32 v[14:15], v[12:13]
	v_mov_b64_e32 v[12:13], v[10:11]
	v_mov_b64_e32 v[10:11], v[8:9]
	v_mov_b64_e32 v[8:9], v[6:7]
	v_mov_b64_e32 v[6:7], v[4:5]
	v_mov_b64_e32 v[4:5], v[2:3]
	v_mov_b64_e32 v[2:3], v[0:1]
	s_mov_b32 s69, 0

; DI int crow(int r, int hi) { return (r & 3) + 8 * (r >> 2) + 4 * hi; }
; #define MFMA32(a, b, c) __builtin_amdgcn_mfma_f32_32x32x16_bf16((a), (b), (c), 0, 0, 0)
; DI void phase_attn(int wid0, const Params& p, int L, unsigned char* lds, bool dry) {
;     ...
;             const int kpos0 = (t == 0) ? 0 : 16 + 32 * (t - 1);
;             if (kpos0 <= wq0 + 31) {
;                 const unsigned char* Ks = lds + 65536 + (t & 1) * 32768 + psub * 8192;
;                 f32x16 p0, p0b;
; #pragma unroll
;                 for (int r = 0; r < 16; ++r) { p0[r] = 0.f; p0b[r] = 0.f; }
;                 int swz = (r32 & 6) << 4, kro = r32 * 256 + ((hi ^ (r32 & 1)) << 4); asm volatile("" : "+v"(swz), "+v"(kro));
; #pragma unroll
;                 for (int d0 = 0; d0 < 8; d0 += 2) {
;                     const bf16x8 b0 = *(const bf16x8*)(Ks + kro + ((d0 * 32) ^ swz));
;                     const bf16x8 qf = *(const bf16x8*)(qlds + d0 * 1024);
;                     const bf16x8 b1 = *(const bf16x8*)(Ks + kro + (((d0 + 1) * 32) ^ swz));
;                     const bf16x8 qg = *(const bf16x8*)(qlds + (d0 + 1) * 1024);
;                     p0 = MFMA32(b0, qf, p0);
;                     p0b = MFMA32(b1, qg, p0b);
;                     if (d0 == 2) __builtin_amdgcn_sched_barrier(0);
;                 }
; #pragma unroll
;                 for (int r = 0; r < 16; ++r) p0[r] += p0b[r];
;                 __builtin_amdgcn_sched_barrier(0);
;                 if (t > 0 && wq0 - (kpos0 + 31) >= 128) {
; #pragma unroll
;                     for (int r = 0; r < 16; ++r) p0[r] = fmaf(p0[r], ATT_C, bfar);
;                 } else {
; #pragma unroll
;                     for (int r = 0; r < 16; ++r) {
;                         const int k0i = crow(r, hi);
;                         const int d0v = qpos - (kpos0 + k0i);
;                         const bool v0 = (d0v >= 0) && (t > 0 || k0i < 16);
;                         const int idx = v0 ? (d0v < 128 ? d0v : 128) : 129;
;                         p0[r] = fmaf(p0[r], ATT_C, tab[idx]);
.Lattn_nodma0:
	s_add_i32 s48, s7, -16
	s_cmp_lg_u32 s69, 0
	s_cselect_b32 s48, s48, 0
	s_cmp_gt_i32 s48, s38
	s_cbranch_scc1 .Lattn_skip0
	ds_read_b128 v[216:219], v188
	ds_read_b128 v[220:223], v177
	ds_read_b128 v[236:239], v209
	ds_read_b128 v[240:243], v210
	s_waitcnt lgkmcnt(3)
	v_mfma_f32_32x32x16_bf16 v[140:155], v[216:219], v[248:251], 0
	ds_read_b128 v[216:219], v211
	s_waitcnt lgkmcnt(3)
	v_mfma_f32_32x32x16_bf16 v[140:155], v[220:223], v[252:255], v[140:155]
	ds_read_b128 v[220:223], v215
	s_waitcnt lgkmcnt(3)
	v_mfma_f32_32x32x16_bf16 v[140:155], v[236:239], v[200:203], v[140:155]
	ds_read_b128 v[236:239], v224
	s_waitcnt lgkmcnt(3)
	v_mfma_f32_32x32x16_bf16 v[140:155], v[240:243], v[204:207], v[140:155]
	ds_read_b128 v[240:243], v225
	s_waitcnt lgkmcnt(3)
	v_mfma_f32_32x32x16_bf16 v[140:155], v[216:219], v[164:167], v[140:155]
	s_waitcnt lgkmcnt(2)
	v_mfma_f32_32x32x16_bf16 v[140:155], v[220:223], v[168:171], v[140:155]
	s_waitcnt lgkmcnt(1)
	v_mfma_f32_32x32x16_bf16 v[140:155], v[236:239], v[172:175], v[140:155]
	s_waitcnt lgkmcnt(0)
	v_mfma_f32_32x32x16_bf16 v[140:155], v[240:243], v[232:235], v[140:155]
	s_cmp_lg_u32 s69, 0
	s_cselect_b64 s[80:81], -1, 0
	s_cmpk_gt_i32 s39, 0x7f
	s_cselect_b64 s[82:83], -1, 0
	s_and_b64 s[82:83], s[80:81], s[82:83]
	s_andn2_b64 vcc, exec, s[82:83]
	s_cbranch_vccz .Lattn_far0
	v_add_u32_e32 v226, s48, v194
	v_sub_u32_e32 v229, v195, v226
	v_sub_u32_e32 v216, v195, v226
	v_cmp_lt_i32_e32 vcc, -1, v216
	s_or_b64 s[82:83], s[10:11], s[80:81]
	v_add_u32_e32 v217, s48, v197
	v_min_i32_e32 v216, 0x80, v216
	s_and_b64 vcc, s[82:83], vcc
	v_sub_u32_e32 v217, v195, v217
	v_cndmask_b32_e32 v216, v187, v216, vcc
	v_cmp_lt_i32_e32 vcc, -1, v217
	s_or_b64 s[82:83], s[12:13], s[80:81]
	v_add_u32_e32 v218, s48, v198
	v_min_i32_e32 v217, 0x80, v217
	s_and_b64 vcc, s[82:83], vcc
	v_sub_u32_e32 v218, v195, v218
	v_cndmask_b32_e32 v217, v187, v217, vcc
	v_cmp_lt_i32_e32 vcc, -1, v218
	s_or_b64 s[82:83], s[14:15], s[80:81]
	v_add_u32_e32 v219, s48, v199
	v_min_i32_e32 v218, 0x80, v218
	s_and_b64 vcc, s[82:83], vcc
	v_sub_u32_e32 v219, v195, v219
	v_cndmask_b32_e32 v218, v187, v218, vcc
	v_cmp_lt_i32_e32 vcc, -1, v219
	s_or_b64 s[82:83], s[16:17], s[80:81]
	v_min_i32_e32 v219, 0x80, v219
	s_and_b64 vcc, s[82:83], vcc
	v_cndmask_b32_e32 v219, v187, v219, vcc
	v_lshl_add_u32 v216, v216, 2, s37
	v_lshl_add_u32 v217, v217, 2, s37
	v_lshl_add_u32 v218, v218, 2, s37
	v_lshl_add_u32 v219, v219, 2, s37
	ds_read_b32 v216, v216
	ds_read_b32 v217, v217
	ds_read_b32 v218, v218
	ds_read_b32 v219, v219
	v_add_u32_e32 v220, -8, v229
	v_cmp_lt_i32_e32 vcc, -1, v220
	s_or_b64 s[82:83], s[18:19], s[80:81]
	v_min_i32_e32 v220, 0x80, v220
	s_and_b64 vcc, s[82:83], vcc
	v_add_u32_e32 v221, -9, v229
	v_cndmask_b32_e32 v220, v187, v220, vcc
	v_cmp_lt_i32_e32 vcc, -1, v221
	v_min_i32_e32 v221, 0x80, v221
	s_and_b64 vcc, s[82:83], vcc
	v_add_u32_e32 v222, -10, v229
	v_cndmask_b32_e32 v221, v187, v221, vcc
	v_cmp_lt_i32_e32 vcc, -1, v222
	v_min_i32_e32 v222, 0x80, v222
	s_and_b64 vcc, s[82:83], vcc
	v_add_u32_e32 v223, -11, v229
	v_cndmask_b32_e32 v222, v187, v222, vcc
	v_cmp_lt_i32_e32 vcc, -1, v223
	v_min_i32_e32 v223, 0x80, v223
	s_and_b64 vcc, s[82:83], vcc
	v_cndmask_b32_e32 v223, v187, v223, vcc
	v_lshl_add_u32 v220, v220, 2, s37
	v_lshl_add_u32 v221, v221, 2, s37
	v_lshl_add_u32 v222, v222, 2, s37
	v_lshl_add_u32 v223, v223, 2, s37
	ds_read_b32 v220, v220
	ds_read_b32 v221, v221
	ds_read_b32 v222, v222
	ds_read_b32 v223, v223
	v_add_u32_e32 v236, -16, v229
	v_cmp_lt_i32_e32 vcc, -1, v236
	s_or_b64 s[82:83], s[20:21], s[80:81]
	v_min_i32_e32 v236, 0x80, v236
	s_and_b64 vcc, s[82:83], vcc
	v_add_u32_e32 v237, 0xffffffef, v229
	v_cndmask_b32_e32 v236, v187, v236, vcc
	v_cmp_lt_i32_e32 vcc, -1, v237
	v_min_i32_e32 v237, 0x80, v237
	s_and_b64 vcc, s[82:83], vcc
	v_add_u32_e32 v238, 0xffffffee, v229
	v_cndmask_b32_e32 v237, v187, v237, vcc
	v_cmp_lt_i32_e32 vcc, -1, v238
	v_min_i32_e32 v238, 0x80, v238
	s_and_b64 vcc, s[82:83], vcc
	v_add_u32_e32 v239, 0xffffffed, v229
	v_cndmask_b32_e32 v238, v187, v238, vcc
	v_cmp_lt_i32_e32 vcc, -1, v239
	v_min_i32_e32 v239, 0x80, v239
	s_and_b64 vcc, s[82:83], vcc
	v_cndmask_b32_e32 v239, v187, v239, vcc
	v_lshl_add_u32 v236, v236, 2, s37
	v_lshl_add_u32 v237, v237, 2, s37
	v_lshl_add_u32 v238, v238, 2, s37
	v_lshl_add_u32 v239, v239, 2, s37
	ds_read_b32 v236, v236
	ds_read_b32 v237, v237
	ds_read_b32 v238, v238
	ds_read_b32 v239, v239
	v_add_u32_e32 v240, 0xffffffe8, v229
	v_cmp_lt_i32_e32 vcc, -1, v240
	s_or_b64 s[80:81], s[22:23], s[80:81]
	v_min_i32_e32 v240, 0x80, v240
	s_and_b64 vcc, s[80:81], vcc
	v_add_u32_e32 v241, 0xffffffe7, v229
	v_cndmask_b32_e32 v240, v187, v240, vcc
	v_cmp_lt_i32_e32 vcc, -1, v241
	v_min_i32_e32 v241, 0x80, v241
	s_and_b64 vcc, s[80:81], vcc
	v_add_u32_e32 v242, 0xffffffe6, v229
	v_cndmask_b32_e32 v241, v187, v241, vcc
	v_cmp_lt_i32_e32 vcc, -1, v242
	v_min_i32_e32 v242, 0x80, v242
	s_and_b64 vcc, s[80:81], vcc
	v_add_u32_e32 v226, 0xffffffe5, v229
	v_cndmask_b32_e32 v242, v187, v242, vcc
	v_cmp_lt_i32_e32 vcc, -1, v226
	v_min_i32_e32 v226, 0x80, v226
	s_and_b64 vcc, s[80:81], vcc
	v_lshl_add_u32 v240, v240, 2, s37
	v_lshl_add_u32 v241, v241, 2, s37
	v_lshl_add_u32 v242, v242, 2, s37
	v_cndmask_b32_e32 v226, v187, v226, vcc
	v_lshl_add_u32 v226, v226, 2, s37
	ds_read_b32 v240, v240
	ds_read_b32 v241, v241
	ds_read_b32 v242, v242
	ds_read_b32 v243, v226
	s_waitcnt lgkmcnt(0)
	v_pk_fma_f32 v[140:141], v[140:141], s[36:37], v[216:217] op_sel_hi:[1,0,1]
	v_pk_fma_f32 v[142:143], v[142:143], s[36:37], v[218:219] op_sel_hi:[1,0,1]
	v_pk_fma_f32 v[144:145], v[144:145], s[36:37], v[220:221] op_sel_hi:[1,0,1]
	v_pk_fma_f32 v[146:147], v[146:147], s[36:37], v[222:223] op_sel_hi:[1,0,1]
	v_pk_fma_f32 v[148:149], v[148:149], s[36:37], v[236:237] op_sel_hi:[1,0,1]
	v_pk_fma_f32 v[150:151], v[150:151], s[36:37], v[238:239] op_sel_hi:[1,0,1]
	v_pk_fma_f32 v[152:153], v[152:153], s[36:37], v[240:241] op_sel_hi:[1,0,1]
	v_pk_fma_f32 v[154:155], v[154:155], s[36:37], v[242:243] op_sel_hi:[1,0,1]
	s_mov_b32 s82, 1.0
	v_mov_b32_e32 v231, 0
	s_branch .Lattn_region0

; DI void phase_attn(int wid0, const Params& p, int L, unsigned char* lds, bool dry) {
;     ...
;                 float pmax = p0[0];
; #pragma unroll
;                 for (int r = 1; r < 16; ++r) pmax = fmaxf(pmax, p0[r]);
;                 { auto rr = __builtin_amdgcn_permlane32_swap(__float_as_uint(pmax), __float_as_uint(pmax), false, false); pmax = fmaxf(__uint_as_float(rr[0]), __uint_as_float(rr[1])); }
;                 float mn, alpha;
;                 if (__all(pmax - m_reg <= ATT_THR2)) { mn = m_reg; alpha = 1.f; }
;                 else { mn = fmaxf(m_reg, pmax); alpha = __builtin_amdgcn_exp2f(m_reg - mn); m_reg = mn; }
;                 float ps = 0.f;
; #pragma unroll
;                 for (int r = 0; r < 16; ++r) { p0[r] = __builtin_amdgcn_exp2f(p0[r] - mn); ps += p0[r]; }
;                 { auto rr = __builtin_amdgcn_permlane32_swap(__float_as_uint(ps), __float_as_uint(ps), false, false); ps = __uint_as_float(rr[0]) + __uint_as_float(rr[1]); }
;                 l_reg = l_reg * alpha + ps;
;                 __builtin_amdgcn_sched_barrier(0);
;                 bf16x8 pa0, pa1;
;     ...
;                 PK4(p0, 0, pa0); PK4(p0, 8, pa1);
;     ...
;                 __builtin_amdgcn_sched_barrier(0);
;                 if (__any(alpha < 1.f)) {
;                     if (hi == 0) al_l[r32] = alpha;
;                     asm volatile("s_waitcnt lgkmcnt(0)" ::: "memory");
;                     float ar[16];
; #pragma unroll
;                     for (int r = 0; r < 16; ++r) ar[r] = al_l[crow(r, hi)];
; #pragma unroll
;                     for (int d = 0; d < 8; ++d)
; #pragma unroll
;                         for (int r = 0; r < 16; ++r) o[d][r] *= ar[r];
;                 }
;                 __builtin_amdgcn_sched_barrier(0);
;                 LAS unsigned char* vbp = ldsl + 65536 + (t & 1) * 32768 + 16384 + v_rd_base(lane);
;                 __builtin_amdgcn_s_setprio(1);
;     ...
;                 {
;                     s16x4 a0, a1, a2, a3, b0_, b1_, b2_, b3_;
;                     PV_RD(0, a0, a1, a2, a3); SB();
;                     PV_RD(1, b0_, b1_, b2_, b3_); SB(); PV_MM(0, a0, a1, a2, a3); SB();
;                     PV_RD(2, a0, a1, a2, a3); SB(); PV_MM(1, b0_, b1_, b2_, b3_); SB();
;                     PV_RD(3, b0_, b1_, b2_, b3_); SB(); PV_MM(2, a0, a1, a2, a3); SB();
;                     PV_RD(4, a0, a1, a2, a3); SB(); PV_MM(3, b0_, b1_, b2_, b3_); SB();
.Lattn_region0:
	v_add_u32_e32 v0, s101, v212
	ds_read_b64_tr_b16 v[216:217], v0 offset:16384
	ds_read_b64_tr_b16 v[218:219], v0 offset:20480
	ds_read_b64_tr_b16 v[220:221], v0 offset:24576
	ds_read_b64_tr_b16 v[222:223], v0 offset:28672
	ds_read_b64_tr_b16 v[236:237], v0 offset:16896
	ds_read_b64_tr_b16 v[238:239], v0 offset:20992
	ds_read_b64_tr_b16 v[240:241], v0 offset:25088
	ds_read_b64_tr_b16 v[242:243], v0 offset:29184
	s_waitcnt lgkmcnt(6)
	v_mfma_f32_32x32x16_bf16 v[114:129], v[132:135], v[216:219], v[114:129]
	s_waitcnt lgkmcnt(4)
	v_mfma_f32_32x32x16_bf16 v[114:129], v[136:139], v[220:223], v[114:129]
	v_max3_f32 v226, v140, v141, v142
	v_max3_f32 v226, v226, v143, v144
	v_max3_f32 v226, v226, v145, v146
	v_max3_f32 v226, v226, v147, v148
	v_max3_f32 v226, v226, v149, v150
	v_max3_f32 v226, v226, v151, v152
	v_max3_f32 v226, v226, v153, v154
	ds_read_b64_tr_b16 v[216:217], v0 offset:17408
	ds_read_b64_tr_b16 v[218:219], v0 offset:21504
	ds_read_b64_tr_b16 v[220:221], v0 offset:25600
	ds_read_b64_tr_b16 v[222:223], v0 offset:29696
	s_waitcnt lgkmcnt(6)
	v_mfma_f32_32x32x16_bf16 v[98:113], v[132:135], v[236:239], v[98:113]
	v_max_f32_e32 v226, v226, v155
	v_mov_b32_e32 v227, v226
	s_nop 1
	v_permlane32_swap_b32_e32 v226, v227
	v_max_f32_e32 v226, v226, v227
	v_fma_f32 v226, v226, s82, v231
	v_sub_f32_e32 v227, v226, v213
	s_mov_b32 s48, 0x4138aa3b
	s_waitcnt lgkmcnt(4)
	v_mfma_f32_32x32x16_bf16 v[98:113], v[136:139], v[240:243], v[98:113]
	v_cmp_ge_f32_e32 vcc, s48, v227
	s_cmp_eq_u64 vcc, exec
	v_max_f32_e32 v226, v213, v226
	s_cselect_b64 vcc, -1, 0
	v_sub_f32_e32 v227, v213, v226
	v_cndmask_b32_e32 v213, v226, v213, vcc
	v_sub_f32_e32 v230, v231, v213
	v_fma_f32 v140, v140, s82, v230
	ds_read_b64_tr_b16 v[236:237], v0 offset:17920
	ds_read_b64_tr_b16 v[238:239], v0 offset:22016
	ds_read_b64_tr_b16 v[240:241], v0 offset:26112
	ds_read_b64_tr_b16 v[242:243], v0 offset:30208
	s_waitcnt lgkmcnt(6)
	v_mfma_f32_32x32x16_bf16 v[82:97], v[132:135], v[216:219], v[82:97]
	v_exp_f32_e32 v140, v140
	v_fma_f32 v141, v141, s82, v230
	v_exp_f32_e32 v141, v141
	v_fma_f32 v142, v142, s82, v230
	v_exp_f32_e32 v142, v142
	s_waitcnt lgkmcnt(4)
	v_mfma_f32_32x32x16_bf16 v[82:97], v[136:139], v[220:223], v[82:97]
	v_add_f32_e32 v226, v140, v141
	v_fma_f32 v143, v143, s82, v230
	v_exp_f32_e32 v143, v143
	v_add_f32_e32 v226, v226, v142
	v_fma_f32 v144, v144, s82, v230
	v_exp_f32_e32 v144, v144
	ds_read_b64_tr_b16 v[216:217], v0 offset:18432
	ds_read_b64_tr_b16 v[218:219], v0 offset:22528
	ds_read_b64_tr_b16 v[220:221], v0 offset:26624
	ds_read_b64_tr_b16 v[222:223], v0 offset:30720
	s_waitcnt lgkmcnt(6)
	v_mfma_f32_32x32x16_bf16 v[66:81], v[132:135], v[236:239], v[66:81]
	v_add_f32_e32 v226, v226, v143
	v_fma_f32 v145, v145, s82, v230
	v_exp_f32_e32 v145, v145
	v_add_f32_e32 v226, v226, v144
	v_fma_f32 v146, v146, s82, v230
	v_exp_f32_e32 v146, v146
	s_waitcnt lgkmcnt(4)
	v_mfma_f32_32x32x16_bf16 v[66:81], v[136:139], v[240:243], v[66:81]
	v_add_f32_e32 v226, v226, v145
	v_fma_f32 v147, v147, s82, v230
	v_exp_f32_e32 v147, v147
	v_add_f32_e32 v226, v226, v146
	v_fma_f32 v148, v148, s82, v230
	v_exp_f32_e32 v148, v148
	ds_read_b64_tr_b16 v[236:237], v0 offset:18944
	ds_read_b64_tr_b16 v[238:239], v0 offset:23040
	ds_read_b64_tr_b16 v[240:241], v0 offset:27136
	ds_read_b64_tr_b16 v[242:243], v0 offset:31232
	s_waitcnt lgkmcnt(6)
	v_mfma_f32_32x32x16_bf16 v[50:65], v[132:135], v[216:219], v[50:65]
	v_add_f32_e32 v226, v226, v147
	v_fma_f32 v149, v149, s82, v230
	v_exp_f32_e32 v149, v149
	v_add_f32_e32 v226, v226, v148
	v_fma_f32 v150, v150, s82, v230
	v_exp_f32_e32 v150, v150
	s_waitcnt lgkmcnt(4)
	v_mfma_f32_32x32x16_bf16 v[50:65], v[136:139], v[220:223], v[50:65]
	v_add_f32_e32 v226, v226, v149
	v_fma_f32 v151, v151, s82, v230
	v_exp_f32_e32 v151, v151
	v_add_f32_e32 v226, v226, v150
	v_fma_f32 v152, v152, s82, v230
	ds_read_b64_tr_b16 v[216:217], v0 offset:19456
	ds_read_b64_tr_b16 v[218:219], v0 offset:23552
	ds_read_b64_tr_b16 v[220:221], v0 offset:27648
	ds_read_b64_tr_b16 v[222:223], v0 offset:31744
	s_waitcnt lgkmcnt(6)
	v_mfma_f32_32x32x16_bf16 v[34:49], v[132:135], v[236:239], v[34:49]
	v_exp_f32_e32 v152, v152
	v_add_f32_e32 v226, v226, v151
	v_fma_f32 v153, v153, s82, v230
	v_exp_f32_e32 v153, v153
	s_waitcnt lgkmcnt(4)
	v_mfma_f32_32x32x16_bf16 v[34:49], v[136:139], v[240:243], v[34:49]
	v_add_f32_e32 v226, v226, v152
	v_fma_f32 v154, v154, s82, v230
	v_exp_f32_e32 v154, v154
	v_add_f32_e32 v226, v226, v153
	v_fma_f32 v155, v155, s82, v230
	ds_read_b64_tr_b16 v[236:237], v0 offset:19968
	ds_read_b64_tr_b16 v[238:239], v0 offset:24064
	ds_read_b64_tr_b16 v[240:241], v0 offset:28160
	ds_read_b64_tr_b16 v[242:243], v0 offset:32256
	s_waitcnt lgkmcnt(6)
	v_mfma_f32_32x32x16_bf16 v[18:33], v[132:135], v[216:219], v[18:33]
	v_exp_f32_e32 v155, v155
	v_add_f32_e32 v226, v226, v154
	v_exp_f32_e32 v227, v227
	v_add_f32_e32 v228, v226, v155
	s_waitcnt lgkmcnt(4)
	v_mfma_f32_32x32x16_bf16 v[18:33], v[136:139], v[220:223], v[18:33]
	v_cndmask_b32_e64 v227, v227, 1.0, vcc
	v_mov_b32_e32 v229, v228
	v_cvt_pk_bf16_f32 v156, v140, v141
	v_cvt_pk_bf16_f32 v157, v142, v143
	v_cvt_pk_bf16_f32 v158, v144, v145
	v_cvt_pk_bf16_f32 v159, v146, v147
	s_waitcnt lgkmcnt(2)
	v_mfma_f32_32x32x16_bf16 v[2:17], v[132:135], v[236:239], v[2:17]
	v_cvt_pk_bf16_f32 v160, v148, v149
	v_cvt_pk_bf16_f32 v161, v150, v151
	v_cvt_pk_bf16_f32 v162, v152, v153
	v_cvt_pk_bf16_f32 v163, v154, v155
	v_permlane32_swap_b32_e32 v228, v229
	v_permlane32_swap_b32_e32 v156, v158
	s_waitcnt lgkmcnt(0)
	v_mfma_f32_32x32x16_bf16 v[2:17], v[136:139], v[240:243], v[2:17]
	v_permlane32_swap_b32_e32 v157, v159
	v_permlane32_swap_b32_e32 v160, v162
	v_permlane32_swap_b32_e32 v161, v163
	v_add_f32_e32 v228, v228, v229
	v_fma_f32 v130, v130, v227, v228
	v_cmp_gt_f32_e32 vcc, 1.0, v227
	s_cbranch_vccz .Lattn_norescale0
; DI int crow(int r, int hi) { return (r & 3) + 8 * (r >> 2) + 4 * hi; }
; DI void phase_attn(int wid0, const Params& p, int L, unsigned char* lds, bool dry) {
;     ...
;                 if (__any(alpha < 1.f)) {
;                     if (hi == 0) al_l[r32] = alpha;
;                     asm volatile("s_waitcnt lgkmcnt(0)" ::: "memory");
;                     float ar[16];
; #pragma unroll
;                     for (int r = 0; r < 16; ++r) ar[r] = al_l[crow(r, hi)];
; #pragma unroll
;                     for (int d = 0; d < 8; ++d)
; #pragma unroll
;                         for (int r = 0; r < 16; ++r) o[d][r] *= ar[r];
;                 }
;                 __builtin_amdgcn_sched_barrier(0);
	s_and_saveexec_b64 s[80:81], s[8:9]
	ds_write_b32 v196, v227 offset:128
	s_or_b64 exec, exec, s[80:81]
	s_waitcnt lgkmcnt(0)
	ds_read_b128 v[152:155], v214 offset:224
	ds_read_b128 v[148:151], v214 offset:192
	ds_read_b128 v[144:147], v214 offset:160
	ds_read_b128 v[140:143], v214 offset:128
	s_waitcnt lgkmcnt(0)
	v_pk_mul_f32 v[126:127], v[126:127], v[152:153]
	v_pk_mul_f32 v[122:123], v[122:123], v[148:149]
	v_pk_mul_f32 v[118:119], v[118:119], v[144:145]
	v_pk_mul_f32 v[128:129], v[128:129], v[154:155]
	v_pk_mul_f32 v[124:125], v[124:125], v[150:151]
	v_pk_mul_f32 v[120:121], v[120:121], v[146:147]
	v_pk_mul_f32 v[116:117], v[116:117], v[142:143]
	v_pk_mul_f32 v[114:115], v[114:115], v[140:141]
	v_pk_mul_f32 v[110:111], v[110:111], v[152:153]
	v_pk_mul_f32 v[106:107], v[106:107], v[148:149]
	v_pk_mul_f32 v[102:103], v[102:103], v[144:145]
	v_pk_mul_f32 v[112:113], v[112:113], v[154:155]
	v_pk_mul_f32 v[108:109], v[108:109], v[150:151]
	v_pk_mul_f32 v[104:105], v[104:105], v[146:147]
	v_pk_mul_f32 v[100:101], v[100:101], v[142:143]
	v_pk_mul_f32 v[98:99], v[98:99], v[140:141]
	v_pk_mul_f32 v[94:95], v[94:95], v[152:153]
	v_pk_mul_f32 v[90:91], v[90:91], v[148:149]
	v_pk_mul_f32 v[86:87], v[86:87], v[144:145]
	v_pk_mul_f32 v[96:97], v[96:97], v[154:155]
	v_pk_mul_f32 v[92:93], v[92:93], v[150:151]
	v_pk_mul_f32 v[88:89], v[88:89], v[146:147]
	v_pk_mul_f32 v[84:85], v[84:85], v[142:143]
	v_pk_mul_f32 v[82:83], v[82:83], v[140:141]
	v_pk_mul_f32 v[78:79], v[78:79], v[152:153]
	v_pk_mul_f32 v[74:75], v[74:75], v[148:149]
	v_pk_mul_f32 v[70:71], v[70:71], v[144:145]
	v_pk_mul_f32 v[80:81], v[80:81], v[154:155]
	v_pk_mul_f32 v[76:77], v[76:77], v[150:151]
	v_pk_mul_f32 v[72:73], v[72:73], v[146:147]
	v_pk_mul_f32 v[68:69], v[68:69], v[142:143]
	v_pk_mul_f32 v[66:67], v[66:67], v[140:141]
	v_pk_mul_f32 v[62:63], v[62:63], v[152:153]
	v_pk_mul_f32 v[58:59], v[58:59], v[148:149]
	v_pk_mul_f32 v[54:55], v[54:55], v[144:145]
	v_pk_mul_f32 v[64:65], v[64:65], v[154:155]
	v_pk_mul_f32 v[60:61], v[60:61], v[150:151]
	v_pk_mul_f32 v[56:57], v[56:57], v[146:147]
	v_pk_mul_f32 v[52:53], v[52:53], v[142:143]
	v_pk_mul_f32 v[50:51], v[50:51], v[140:141]
	v_pk_mul_f32 v[46:47], v[46:47], v[152:153]
	v_pk_mul_f32 v[42:43], v[42:43], v[148:149]
	v_pk_mul_f32 v[38:39], v[38:39], v[144:145]
	v_pk_mul_f32 v[48:49], v[48:49], v[154:155]
	v_pk_mul_f32 v[44:45], v[44:45], v[150:151]
	v_pk_mul_f32 v[40:41], v[40:41], v[146:147]
	v_pk_mul_f32 v[36:37], v[36:37], v[142:143]
	v_pk_mul_f32 v[34:35], v[34:35], v[140:141]
	v_pk_mul_f32 v[30:31], v[30:31], v[152:153]
	v_pk_mul_f32 v[26:27], v[26:27], v[148:149]
	v_pk_mul_f32 v[22:23], v[22:23], v[144:145]
	v_pk_mul_f32 v[32:33], v[32:33], v[154:155]
	v_pk_mul_f32 v[28:29], v[28:29], v[150:151]
	v_pk_mul_f32 v[24:25], v[24:25], v[146:147]
	v_pk_mul_f32 v[20:21], v[20:21], v[142:143]
	v_pk_mul_f32 v[18:19], v[18:19], v[140:141]
	v_pk_mul_f32 v[14:15], v[14:15], v[152:153]
	v_pk_mul_f32 v[10:11], v[10:11], v[148:149]
	v_pk_mul_f32 v[6:7], v[6:7], v[144:145]
	v_pk_mul_f32 v[16:17], v[16:17], v[154:155]
	v_pk_mul_f32 v[12:13], v[12:13], v[150:151]
	v_pk_mul_f32 v[8:9], v[8:9], v[146:147]
	v_pk_mul_f32 v[4:5], v[4:5], v[142:143]
	v_pk_mul_f32 v[2:3], v[2:3], v[140:141]
.Lattn_norescale0:
	s_or_b32 s100, s100, 0x100
	s_branch .Lattn_latch0

; #define LAS __attribute__((address_space(3)))
; DI void attn_stage(const bf16_t* kbase, const bf16_t* vbase, unsigned koff, unsigned voff, LAS unsigned char* ldsbuf, int wid) {
; #pragma unroll
;     for (int i = 0; i < 2; ++i) {
;         const char* src = (const char*)kbase + (size_t)(i * 128) * 2;
;         __builtin_amdgcn_global_load_lds((const unsigned*)(src + koff), (LAS unsigned*)(ldsbuf + (wid + 8 * i) * 1024), 16, 0, 0);
;     }
; #pragma unroll
;     for (int i = 0; i < 2; ++i) {
;         const char* src = (const char*)vbase + (size_t)(16 * i * 2048) * 2;
;         __builtin_amdgcn_global_load_lds((const unsigned*)(src + voff), (LAS unsigned*)(ldsbuf + 16384 + (wid + 8 * i) * 1024), 16, 0, 0);
;     }
; }
; DI void phase_attn(int wid0, const Params& p, int L, unsigned char* lds, bool dry) {
;     ...
;         for (int t = 0; t < ntiles; ++t) {
;             asm volatile("s_waitcnt vmcnt(0) lgkmcnt(0)" ::: "memory"); __builtin_amdgcn_s_barrier(); asm volatile("" ::: "memory");
;             if (t + 1 < ntiles) attn_stage(kh_ + (size_t)(b * 4096 + 32 * t) * 2048, vh_ + (size_t)(b * 4096 + 32 * t) * 2048, koff, voff, ldsl + 65536 + ((t + 1) & 1) * 32768, wid);
.Lattn_latch0:
	s_and_b32 s82, s100, 3
	s_lshl_b32 s101, s82, 15
	s_add_i32 s82, s82, 1
	s_cmp_eq_u32 s82, 3
	s_cselect_b32 s82, 0, s82
	s_andn2_b32 s100, s100, 3
	s_or_b32 s100, s100, s82
	s_add_i32 s66, s66, 0x8000
	s_sub_i32 s39, s39, 32
	s_add_i32 s7, s7, 32
	s_cmp_eq_u32 s6, s67
	s_cbranch_scc1 .Lattn_exit0
	s_mov_b32 s69, s67
.Lattn_top1:
	s_waitcnt vmcnt(0) lgkmcnt(0)
	s_barrier
	s_add_i32 s67, s69, 1
	s_cmp_ge_i32 s67, s6
	s_cbranch_scc1 .Lattn_nodma1
	s_add_i32 s80, s40, s7
	s_add_i32 s48, s66, 0x8000
	s_ashr_i32 s81, s80, 31
	s_and_b32 s48, s48, 0x8000
	s_lshl_b64 s[80:81], s[80:81], 12
	s_add_i32 s48, s4, s48
	s_add_u32 s88, s84, s80
	s_addc_u32 s89, s85, s81
	s_add_u32 s90, s88, 0x100
	s_addc_u32 s91, s89, 0
	s_add_u32 s92, s86, s80
	s_addc_u32 s93, s87, s81
	s_add_u32 s94, s92, 0x10000
	s_addc_u32 s95, s93, 0
	s_and_b32 s82, s100, 3
	s_add_i32 s82, s82, 1
	s_cmp_eq_u32 s82, 3
	s_cselect_b32 s82, 0, s82
	s_lshl_b32 s82, s82, 15
	s_add_i32 s82, s4, s82
	s_mov_b32 m0, s48
	s_nop 0
	global_load_lds_dwordx4 v131, s[88:89]
	s_add_i32 m0, s48, 0x2000
	s_nop 0
	global_load_lds_dwordx4 v131, s[90:91]
	s_add_i32 m0, s82, 0x4000
	s_nop 0
	global_load_lds_dwordx4 v208, s[92:93]
	s_add_i32 m0, s82, 0x6000
	s_nop 0
	global_load_lds_dwordx4 v208, s[94:95]
; DI int crow(int r, int hi) { return (r & 3) + 8 * (r >> 2) + 4 * hi; }
; #define MFMA32(a, b, c) __builtin_amdgcn_mfma_f32_32x32x16_bf16((a), (b), (c), 0, 0, 0)
; DI void phase_attn(int wid0, const Params& p, int L, unsigned char* lds, bool dry) {
;     ...
;             const int kpos0 = (t == 0) ? 0 : 16 + 32 * (t - 1);
;             if (kpos0 <= wq0 + 31) {
;                 const unsigned char* Ks = lds + 65536 + (t & 1) * 32768 + psub * 8192;
;                 f32x16 p0, p0b;
; #pragma unroll
;                 for (int r = 0; r < 16; ++r) { p0[r] = 0.f; p0b[r] = 0.f; }
;                 int swz = (r32 & 6) << 4, kro = r32 * 256 + ((hi ^ (r32 & 1)) << 4); asm volatile("" : "+v"(swz), "+v"(kro));
; #pragma unroll
;                 for (int d0 = 0; d0 < 8; d0 += 2) {
;                     const bf16x8 b0 = *(const bf16x8*)(Ks + kro + ((d0 * 32) ^ swz));
;                     const bf16x8 qf = *(const bf16x8*)(qlds + d0 * 1024);
;                     const bf16x8 b1 = *(const bf16x8*)(Ks + kro + (((d0 + 1) * 32) ^ swz));
;                     const bf16x8 qg = *(const bf16x8*)(qlds + (d0 + 1) * 1024);
;                     p0 = MFMA32(b0, qf, p0);
;                     p0b = MFMA32(b1, qg, p0b);
;                     if (d0 == 2) __builtin_amdgcn_sched_barrier(0);
;                 }
; #pragma unroll
;                 for (int r = 0; r < 16; ++r) p0[r] += p0b[r];
;                 __builtin_amdgcn_sched_barrier(0);
;                 if (t > 0 && wq0 - (kpos0 + 31) >= 128) {
; #pragma unroll
;                     for (int r = 0; r < 16; ++r) p0[r] = fmaf(p0[r], ATT_C, bfar);
;                 } else {
; #pragma unroll
;                     for (int r = 0; r < 16; ++r) {
;                         const int k0i = crow(r, hi);
;                         const int d0v = qpos - (kpos0 + k0i);
;                         const bool v0 = (d0v >= 0) && (t > 0 || k0i < 16);
;                         const int idx = v0 ? (d0v < 128 ? d0v : 128) : 129;
;                         p0[r] = fmaf(p0[r], ATT_C, tab[idx]);
.Lattn_nodma1:
	s_add_i32 s48, s7, -16
	s_cmp_lg_u32 s69, 0
	s_cselect_b32 s48, s48, 0
	s_cmp_gt_i32 s48, s38
	s_cbranch_scc1 .Lattn_skip1
	ds_read_b128 v[216:219], v188 offset:32768
	ds_read_b128 v[220:223], v177 offset:32768
	ds_read_b128 v[236:239], v209 offset:32768
	ds_read_b128 v[240:243], v210 offset:32768
	s_waitcnt lgkmcnt(3)
	v_mfma_f32_32x32x16_bf16 v[140:155], v[216:219], v[248:251], 0
	ds_read_b128 v[216:219], v211 offset:32768
	s_waitcnt lgkmcnt(3)
	v_mfma_f32_32x32x16_bf16 v[140:155], v[220:223], v[252:255], v[140:155]
	ds_read_b128 v[220:223], v215 offset:32768
	s_waitcnt lgkmcnt(3)
	v_mfma_f32_32x32x16_bf16 v[140:155], v[236:239], v[200:203], v[140:155]
	ds_read_b128 v[236:239], v224 offset:32768
	s_waitcnt lgkmcnt(3)
	v_mfma_f32_32x32x16_bf16 v[140:155], v[240:243], v[204:207], v[140:155]
	ds_read_b128 v[240:243], v225 offset:32768
	s_waitcnt lgkmcnt(3)
	v_mfma_f32_32x32x16_bf16 v[140:155], v[216:219], v[164:167], v[140:155]
	s_waitcnt lgkmcnt(2)
	v_mfma_f32_32x32x16_bf16 v[140:155], v[220:223], v[168:171], v[140:155]
	s_waitcnt lgkmcnt(1)
	v_mfma_f32_32x32x16_bf16 v[140:155], v[236:239], v[172:175], v[140:155]
	s_waitcnt lgkmcnt(0)
	v_mfma_f32_32x32x16_bf16 v[140:155], v[240:243], v[232:235], v[140:155]
	s_cmp_lg_u32 s69, 0
	s_cselect_b64 s[80:81], -1, 0
	s_cmpk_gt_i32 s39, 0x7f
	s_cselect_b64 s[82:83], -1, 0
	s_and_b64 s[82:83], s[80:81], s[82:83]
	s_andn2_b64 vcc, exec, s[82:83]
	s_cbranch_vccz .Lattn_far1
	v_add_u32_e32 v226, s48, v194
	v_sub_u32_e32 v229, v195, v226
	v_sub_u32_e32 v216, v195, v226
	v_cmp_lt_i32_e32 vcc, -1, v216
	s_or_b64 s[82:83], s[10:11], s[80:81]
	v_add_u32_e32 v217, s48, v197
	v_min_i32_e32 v216, 0x80, v216
	s_and_b64 vcc, s[82:83], vcc
	v_sub_u32_e32 v217, v195, v217
	v_cndmask_b32_e32 v216, v187, v216, vcc
	v_cmp_lt_i32_e32 vcc, -1, v217
	s_or_b64 s[82:83], s[12:13], s[80:81]
	v_add_u32_e32 v218, s48, v198
	v_min_i32_e32 v217, 0x80, v217
	s_and_b64 vcc, s[82:83], vcc
	v_sub_u32_e32 v218, v195, v218
	v_cndmask_b32_e32 v217, v187, v217, vcc
	v_cmp_lt_i32_e32 vcc, -1, v218
	s_or_b64 s[82:83], s[14:15], s[80:81]
	v_add_u32_e32 v219, s48, v199
	v_min_i32_e32 v218, 0x80, v218
	s_and_b64 vcc, s[82:83], vcc
	v_sub_u32_e32 v219, v195, v219
	v_cndmask_b32_e32 v218, v187, v218, vcc
	v_cmp_lt_i32_e32 vcc, -1, v219
	s_or_b64 s[82:83], s[16:17], s[80:81]
	v_min_i32_e32 v219, 0x80, v219
	s_and_b64 vcc, s[82:83], vcc
	v_cndmask_b32_e32 v219, v187, v219, vcc
	v_lshl_add_u32 v216, v216, 2, s37
	v_lshl_add_u32 v217, v217, 2, s37
	v_lshl_add_u32 v218, v218, 2, s37
	v_lshl_add_u32 v219, v219, 2, s37
	ds_read_b32 v216, v216
	ds_read_b32 v217, v217
	ds_read_b32 v218, v218
	ds_read_b32 v219, v219
	v_add_u32_e32 v220, -8, v229
	v_cmp_lt_i32_e32 vcc, -1, v220
	s_or_b64 s[82:83], s[18:19], s[80:81]
	v_min_i32_e32 v220, 0x80, v220
	s_and_b64 vcc, s[82:83], vcc
	v_add_u32_e32 v221, -9, v229
	v_cndmask_b32_e32 v220, v187, v220, vcc
	v_cmp_lt_i32_e32 vcc, -1, v221
	v_min_i32_e32 v221, 0x80, v221
	s_and_b64 vcc, s[82:83], vcc
	v_add_u32_e32 v222, -10, v229
	v_cndmask_b32_e32 v221, v187, v221, vcc
	v_cmp_lt_i32_e32 vcc, -1, v222
	v_min_i32_e32 v222, 0x80, v222
	s_and_b64 vcc, s[82:83], vcc
	v_add_u32_e32 v223, -11, v229
	v_cndmask_b32_e32 v222, v187, v222, vcc
	v_cmp_lt_i32_e32 vcc, -1, v223
	v_min_i32_e32 v223, 0x80, v223
	s_and_b64 vcc, s[82:83], vcc
	v_cndmask_b32_e32 v223, v187, v223, vcc
	v_lshl_add_u32 v220, v220, 2, s37
	v_lshl_add_u32 v221, v221, 2, s37
	v_lshl_add_u32 v222, v222, 2, s37
	v_lshl_add_u32 v223, v223, 2, s37
	ds_read_b32 v220, v220
	ds_read_b32 v221, v221
	ds_read_b32 v222, v222
	ds_read_b32 v223, v223
	v_add_u32_e32 v236, -16, v229
	v_cmp_lt_i32_e32 vcc, -1, v236
	s_or_b64 s[82:83], s[20:21], s[80:81]
	v_min_i32_e32 v236, 0x80, v236
	s_and_b64 vcc, s[82:83], vcc
	v_add_u32_e32 v237, 0xffffffef, v229
	v_cndmask_b32_e32 v236, v187, v236, vcc
	v_cmp_lt_i32_e32 vcc, -1, v237
	v_min_i32_e32 v237, 0x80, v237
	s_and_b64 vcc, s[82:83], vcc
	v_add_u32_e32 v238, 0xffffffee, v229
	v_cndmask_b32_e32 v237, v187, v237, vcc
	v_cmp_lt_i32_e32 vcc, -1, v238
	v_min_i32_e32 v238, 0x80, v238
	s_and_b64 vcc, s[82:83], vcc
	v_add_u32_e32 v239, 0xffffffed, v229
	v_cndmask_b32_e32 v238, v187, v238, vcc
	v_cmp_lt_i32_e32 vcc, -1, v239
	v_min_i32_e32 v239, 0x80, v239
	s_and_b64 vcc, s[82:83], vcc
	v_cndmask_b32_e32 v239, v187, v239, vcc
	v_lshl_add_u32 v236, v236, 2, s37
	v_lshl_add_u32 v237, v237, 2, s37
	v_lshl_add_u32 v238, v238, 2, s37
	v_lshl_add_u32 v239, v239, 2, s37
	ds_read_b32 v236, v236
	ds_read_b32 v237, v237
	ds_read_b32 v238, v238
	ds_read_b32 v239, v239
	v_add_u32_e32 v240, 0xffffffe8, v229
	v_cmp_lt_i32_e32 vcc, -1, v240
	s_or_b64 s[80:81], s[22:23], s[80:81]
	v_min_i32_e32 v240, 0x80, v240
	s_and_b64 vcc, s[80:81], vcc
	v_add_u32_e32 v241, 0xffffffe7, v229
	v_cndmask_b32_e32 v240, v187, v240, vcc
	v_cmp_lt_i32_e32 vcc, -1, v241
	v_min_i32_e32 v241, 0x80, v241
	s_and_b64 vcc, s[80:81], vcc
	v_add_u32_e32 v242, 0xffffffe6, v229
	v_cndmask_b32_e32 v241, v187, v241, vcc
	v_cmp_lt_i32_e32 vcc, -1, v242
	v_min_i32_e32 v242, 0x80, v242
	s_and_b64 vcc, s[80:81], vcc
	v_add_u32_e32 v226, 0xffffffe5, v229
	v_cndmask_b32_e32 v242, v187, v242, vcc
	v_cmp_lt_i32_e32 vcc, -1, v226
	v_min_i32_e32 v226, 0x80, v226
	s_and_b64 vcc, s[80:81], vcc
	v_lshl_add_u32 v240, v240, 2, s37
	v_lshl_add_u32 v241, v241, 2, s37
	v_lshl_add_u32 v242, v242, 2, s37
	v_cndmask_b32_e32 v226, v187, v226, vcc
	v_lshl_add_u32 v226, v226, 2, s37
	ds_read_b32 v240, v240
	ds_read_b32 v241, v241
	ds_read_b32 v242, v242
	ds_read_b32 v243, v226
	s_waitcnt lgkmcnt(0)
	v_pk_fma_f32 v[140:141], v[140:141], s[36:37], v[216:217] op_sel_hi:[1,0,1]
	v_pk_fma_f32 v[142:143], v[142:143], s[36:37], v[218:219] op_sel_hi:[1,0,1]
	v_pk_fma_f32 v[144:145], v[144:145], s[36:37], v[220:221] op_sel_hi:[1,0,1]
	v_pk_fma_f32 v[146:147], v[146:147], s[36:37], v[222:223] op_sel_hi:[1,0,1]
	v_pk_fma_f32 v[148:149], v[148:149], s[36:37], v[236:237] op_sel_hi:[1,0,1]
	v_pk_fma_f32 v[150:151], v[150:151], s[36:37], v[238:239] op_sel_hi:[1,0,1]
	v_pk_fma_f32 v[152:153], v[152:153], s[36:37], v[240:241] op_sel_hi:[1,0,1]
	v_pk_fma_f32 v[154:155], v[154:155], s[36:37], v[242:243] op_sel_hi:[1,0,1]
	s_mov_b32 s82, 1.0
	v_mov_b32_e32 v231, 0
	s_branch .Lattn_region1

; DI void phase_attn(int wid0, const Params& p, int L, unsigned char* lds, bool dry) {
;     ...
;                 float pmax = p0[0];
; #pragma unroll
;                 for (int r = 1; r < 16; ++r) pmax = fmaxf(pmax, p0[r]);
;                 { auto rr = __builtin_amdgcn_permlane32_swap(__float_as_uint(pmax), __float_as_uint(pmax), false, false); pmax = fmaxf(__uint_as_float(rr[0]), __uint_as_float(rr[1])); }
;                 float mn, alpha;
;                 if (__all(pmax - m_reg <= ATT_THR2)) { mn = m_reg; alpha = 1.f; }
;                 else { mn = fmaxf(m_reg, pmax); alpha = __builtin_amdgcn_exp2f(m_reg - mn); m_reg = mn; }
;                 float ps = 0.f;
; #pragma unroll
;                 for (int r = 0; r < 16; ++r) { p0[r] = __builtin_amdgcn_exp2f(p0[r] - mn); ps += p0[r]; }
;                 { auto rr = __builtin_amdgcn_permlane32_swap(__float_as_uint(ps), __float_as_uint(ps), false, false); ps = __uint_as_float(rr[0]) + __uint_as_float(rr[1]); }
;                 l_reg = l_reg * alpha + ps;
;                 __builtin_amdgcn_sched_barrier(0);
;                 bf16x8 pa0, pa1;
;     ...
;                 PK4(p0, 0, pa0); PK4(p0, 8, pa1);
;     ...
;                 __builtin_amdgcn_sched_barrier(0);
;                 if (__any(alpha < 1.f)) {
;                     if (hi == 0) al_l[r32] = alpha;
;                     asm volatile("s_waitcnt lgkmcnt(0)" ::: "memory");
;                     float ar[16];
; #pragma unroll
;                     for (int r = 0; r < 16; ++r) ar[r] = al_l[crow(r, hi)];
; #pragma unroll
;                     for (int d = 0; d < 8; ++d)
; #pragma unroll
;                         for (int r = 0; r < 16; ++r) o[d][r] *= ar[r];
;                 }
;                 __builtin_amdgcn_sched_barrier(0);
;                 LAS unsigned char* vbp = ldsl + 65536 + (t & 1) * 32768 + 16384 + v_rd_base(lane);
;                 __builtin_amdgcn_s_setprio(1);
;     ...
;                 {
;                     s16x4 a0, a1, a2, a3, b0_, b1_, b2_, b3_;
;                     PV_RD(0, a0, a1, a2, a3); SB();
;                     PV_RD(1, b0_, b1_, b2_, b3_); SB(); PV_MM(0, a0, a1, a2, a3); SB();
;                     PV_RD(2, a0, a1, a2, a3); SB(); PV_MM(1, b0_, b1_, b2_, b3_); SB();
;                     PV_RD(3, b0_, b1_, b2_, b3_); SB(); PV_MM(2, a0, a1, a2, a3); SB();
;                     PV_RD(4, a0, a1, a2, a3); SB(); PV_MM(3, b0_, b1_, b2_, b3_); SB();
.Lattn_region1:
	v_add_u32_e32 v0, s101, v212
	ds_read_b64_tr_b16 v[216:217], v0 offset:16384
	ds_read_b64_tr_b16 v[218:219], v0 offset:20480
	ds_read_b64_tr_b16 v[220:221], v0 offset:24576
	ds_read_b64_tr_b16 v[222:223], v0 offset:28672
	ds_read_b64_tr_b16 v[236:237], v0 offset:16896
	ds_read_b64_tr_b16 v[238:239], v0 offset:20992
	ds_read_b64_tr_b16 v[240:241], v0 offset:25088
	ds_read_b64_tr_b16 v[242:243], v0 offset:29184
	s_waitcnt lgkmcnt(6)
	v_mfma_f32_32x32x16_bf16 v[114:129], v[156:159], v[216:219], v[114:129]
	s_waitcnt lgkmcnt(4)
	v_mfma_f32_32x32x16_bf16 v[114:129], v[160:163], v[220:223], v[114:129]
	v_max3_f32 v226, v140, v141, v142
	v_max3_f32 v226, v226, v143, v144
	v_max3_f32 v226, v226, v145, v146
	v_max3_f32 v226, v226, v147, v148
	v_max3_f32 v226, v226, v149, v150
	v_max3_f32 v226, v226, v151, v152
	v_max3_f32 v226, v226, v153, v154
	ds_read_b64_tr_b16 v[216:217], v0 offset:17408
	ds_read_b64_tr_b16 v[218:219], v0 offset:21504
	ds_read_b64_tr_b16 v[220:221], v0 offset:25600
	ds_read_b64_tr_b16 v[222:223], v0 offset:29696
	s_waitcnt lgkmcnt(6)
	v_mfma_f32_32x32x16_bf16 v[98:113], v[156:159], v[236:239], v[98:113]
	v_max_f32_e32 v226, v226, v155
	v_mov_b32_e32 v227, v226
	s_nop 1
	v_permlane32_swap_b32_e32 v226, v227
	v_max_f32_e32 v226, v226, v227
	v_fma_f32 v226, v226, s82, v231
	v_sub_f32_e32 v227, v226, v213
	s_mov_b32 s48, 0x4138aa3b
	s_waitcnt lgkmcnt(4)
	v_mfma_f32_32x32x16_bf16 v[98:113], v[160:163], v[240:243], v[98:113]
	v_cmp_ge_f32_e32 vcc, s48, v227
	s_cmp_eq_u64 vcc, exec
	v_max_f32_e32 v226, v213, v226
	s_cselect_b64 vcc, -1, 0
	v_sub_f32_e32 v227, v213, v226
	v_cndmask_b32_e32 v213, v226, v213, vcc
	v_sub_f32_e32 v230, v231, v213
	v_fma_f32 v140, v140, s82, v230
	ds_read_b64_tr_b16 v[236:237], v0 offset:17920
	ds_read_b64_tr_b16 v[238:239], v0 offset:22016
	ds_read_b64_tr_b16 v[240:241], v0 offset:26112
	ds_read_b64_tr_b16 v[242:243], v0 offset:30208
	s_waitcnt lgkmcnt(6)
	v_mfma_f32_32x32x16_bf16 v[82:97], v[156:159], v[216:219], v[82:97]
	v_exp_f32_e32 v140, v140
	v_fma_f32 v141, v141, s82, v230
	v_exp_f32_e32 v141, v141
	v_fma_f32 v142, v142, s82, v230
	v_exp_f32_e32 v142, v142
	s_waitcnt lgkmcnt(4)
	v_mfma_f32_32x32x16_bf16 v[82:97], v[160:163], v[220:223], v[82:97]
	v_add_f32_e32 v226, v140, v141
	v_fma_f32 v143, v143, s82, v230
	v_exp_f32_e32 v143, v143
	v_add_f32_e32 v226, v226, v142
	v_fma_f32 v144, v144, s82, v230
	v_exp_f32_e32 v144, v144
	ds_read_b64_tr_b16 v[216:217], v0 offset:18432
	ds_read_b64_tr_b16 v[218:219], v0 offset:22528
	ds_read_b64_tr_b16 v[220:221], v0 offset:26624
	ds_read_b64_tr_b16 v[222:223], v0 offset:30720
	s_waitcnt lgkmcnt(6)
	v_mfma_f32_32x32x16_bf16 v[66:81], v[156:159], v[236:239], v[66:81]
	v_add_f32_e32 v226, v226, v143
	v_fma_f32 v145, v145, s82, v230
	v_exp_f32_e32 v145, v145
	v_add_f32_e32 v226, v226, v144
	v_fma_f32 v146, v146, s82, v230
	v_exp_f32_e32 v146, v146
	s_waitcnt lgkmcnt(4)
	v_mfma_f32_32x32x16_bf16 v[66:81], v[160:163], v[240:243], v[66:81]
	v_add_f32_e32 v226, v226, v145
	v_fma_f32 v147, v147, s82, v230
	v_exp_f32_e32 v147, v147
	v_add_f32_e32 v226, v226, v146
	v_fma_f32 v148, v148, s82, v230
	v_exp_f32_e32 v148, v148
	ds_read_b64_tr_b16 v[236:237], v0 offset:18944
	ds_read_b64_tr_b16 v[238:239], v0 offset:23040
	ds_read_b64_tr_b16 v[240:241], v0 offset:27136
	ds_read_b64_tr_b16 v[242:243], v0 offset:31232
	s_waitcnt lgkmcnt(6)
	v_mfma_f32_32x32x16_bf16 v[50:65], v[156:159], v[216:219], v[50:65]
	v_add_f32_e32 v226, v226, v147
	v_fma_f32 v149, v149, s82, v230
	v_exp_f32_e32 v149, v149
	v_add_f32_e32 v226, v226, v148
	v_fma_f32 v150, v150, s82, v230
	v_exp_f32_e32 v150, v150
	s_waitcnt lgkmcnt(4)
	v_mfma_f32_32x32x16_bf16 v[50:65], v[160:163], v[220:223], v[50:65]
	v_add_f32_e32 v226, v226, v149
	v_fma_f32 v151, v151, s82, v230
	v_exp_f32_e32 v151, v151
	v_add_f32_e32 v226, v226, v150
	v_fma_f32 v152, v152, s82, v230
	ds_read_b64_tr_b16 v[216:217], v0 offset:19456
	ds_read_b64_tr_b16 v[218:219], v0 offset:23552
	ds_read_b64_tr_b16 v[220:221], v0 offset:27648
	ds_read_b64_tr_b16 v[222:223], v0 offset:31744
	s_waitcnt lgkmcnt(6)
	v_mfma_f32_32x32x16_bf16 v[34:49], v[156:159], v[236:239], v[34:49]
	v_exp_f32_e32 v152, v152
	v_add_f32_e32 v226, v226, v151
	v_fma_f32 v153, v153, s82, v230
	v_exp_f32_e32 v153, v153
	s_waitcnt lgkmcnt(4)
	v_mfma_f32_32x32x16_bf16 v[34:49], v[160:163], v[240:243], v[34:49]
	v_add_f32_e32 v226, v226, v152
	v_fma_f32 v154, v154, s82, v230
	v_exp_f32_e32 v154, v154
	v_add_f32_e32 v226, v226, v153
	v_fma_f32 v155, v155, s82, v230
	ds_read_b64_tr_b16 v[236:237], v0 offset:19968
	ds_read_b64_tr_b16 v[238:239], v0 offset:24064
	ds_read_b64_tr_b16 v[240:241], v0 offset:28160
	ds_read_b64_tr_b16 v[242:243], v0 offset:32256
	s_waitcnt lgkmcnt(6)
	v_mfma_f32_32x32x16_bf16 v[18:33], v[156:159], v[216:219], v[18:33]
	v_exp_f32_e32 v155, v155
	v_add_f32_e32 v226, v226, v154
	v_exp_f32_e32 v227, v227
	v_add_f32_e32 v228, v226, v155
	s_waitcnt lgkmcnt(4)
	v_mfma_f32_32x32x16_bf16 v[18:33], v[160:163], v[220:223], v[18:33]
	v_cndmask_b32_e64 v227, v227, 1.0, vcc
	v_mov_b32_e32 v229, v228
	v_cvt_pk_bf16_f32 v132, v140, v141
	v_cvt_pk_bf16_f32 v133, v142, v143
	v_cvt_pk_bf16_f32 v134, v144, v145
	v_cvt_pk_bf16_f32 v135, v146, v147
	s_waitcnt lgkmcnt(2)
	v_mfma_f32_32x32x16_bf16 v[2:17], v[156:159], v[236:239], v[2:17]
	v_cvt_pk_bf16_f32 v136, v148, v149
	v_cvt_pk_bf16_f32 v137, v150, v151
	v_cvt_pk_bf16_f32 v138, v152, v153
	v_cvt_pk_bf16_f32 v139, v154, v155
	v_permlane32_swap_b32_e32 v228, v229
	v_permlane32_swap_b32_e32 v132, v134
	s_waitcnt lgkmcnt(0)
	v_mfma_f32_32x32x16_bf16 v[2:17], v[160:163], v[240:243], v[2:17]
	v_permlane32_swap_b32_e32 v133, v135
	v_permlane32_swap_b32_e32 v136, v138
	v_permlane32_swap_b32_e32 v137, v139
	v_add_f32_e32 v228, v228, v229
	v_fma_f32 v130, v130, v227, v228
	v_cmp_gt_f32_e32 vcc, 1.0, v227
	s_cbranch_vccz .Lattn_norescale1
; DI int crow(int r, int hi) { return (r & 3) + 8 * (r >> 2) + 4 * hi; }
; DI void phase_attn(int wid0, const Params& p, int L, unsigned char* lds, bool dry) {
;     ...
;                 if (__any(alpha < 1.f)) {
;                     if (hi == 0) al_l[r32] = alpha;
;                     asm volatile("s_waitcnt lgkmcnt(0)" ::: "memory");
;                     float ar[16];
; #pragma unroll
;                     for (int r = 0; r < 16; ++r) ar[r] = al_l[crow(r, hi)];
; #pragma unroll
;                     for (int d = 0; d < 8; ++d)
; #pragma unroll
;                         for (int r = 0; r < 16; ++r) o[d][r] *= ar[r];
;                 }
	s_and_saveexec_b64 s[80:81], s[8:9]
	ds_write_b32 v196, v227 offset:128
	s_or_b64 exec, exec, s[80:81]
	s_waitcnt lgkmcnt(0)
	ds_read_b128 v[152:155], v214 offset:224
	ds_read_b128 v[148:151], v214 offset:192
	ds_read_b128 v[144:147], v214 offset:160
	ds_read_b128 v[140:143], v214 offset:128
	s_waitcnt lgkmcnt(0)
	v_pk_mul_f32 v[126:127], v[126:127], v[152:153]
	v_pk_mul_f32 v[122:123], v[122:123], v[148:149]
	v_pk_mul_f32 v[118:119], v[118:119], v[144:145]
	v_pk_mul_f32 v[128:129], v[128:129], v[154:155]
	v_pk_mul_f32 v[124:125], v[124:125], v[150:151]
	v_pk_mul_f32 v[120:121], v[120:121], v[146:147]
	v_pk_mul_f32 v[116:117], v[116:117], v[142:143]
	v_pk_mul_f32 v[114:115], v[114:115], v[140:141]
	v_pk_mul_f32 v[110:111], v[110:111], v[152:153]
	v_pk_mul_f32 v[106:107], v[106:107], v[148:149]
	v_pk_mul_f32 v[102:103], v[102:103], v[144:145]
	v_pk_mul_f32 v[112:113], v[112:113], v[154:155]
	v_pk_mul_f32 v[108:109], v[108:109], v[150:151]
	v_pk_mul_f32 v[104:105], v[104:105], v[146:147]
	v_pk_mul_f32 v[100:101], v[100:101], v[142:143]
	v_pk_mul_f32 v[98:99], v[98:99], v[140:141]
	v_pk_mul_f32 v[94:95], v[94:95], v[152:153]
	v_pk_mul_f32 v[90:91], v[90:91], v[148:149]
	v_pk_mul_f32 v[86:87], v[86:87], v[144:145]
	v_pk_mul_f32 v[96:97], v[96:97], v[154:155]
	v_pk_mul_f32 v[92:93], v[92:93], v[150:151]
	v_pk_mul_f32 v[88:89], v[88:89], v[146:147]
	v_pk_mul_f32 v[84:85], v[84:85], v[142:143]
	v_pk_mul_f32 v[82:83], v[82:83], v[140:141]
	v_pk_mul_f32 v[78:79], v[78:79], v[152:153]
	v_pk_mul_f32 v[74:75], v[74:75], v[148:149]
	v_pk_mul_f32 v[70:71], v[70:71], v[144:145]
	v_pk_mul_f32 v[80:81], v[80:81], v[154:155]
	v_pk_mul_f32 v[76:77], v[76:77], v[150:151]
	v_pk_mul_f32 v[72:73], v[72:73], v[146:147]
	v_pk_mul_f32 v[68:69], v[68:69], v[142:143]
	v_pk_mul_f32 v[66:67], v[66:67], v[140:141]
	v_pk_mul_f32 v[62:63], v[62:63], v[152:153]
	v_pk_mul_f32 v[58:59], v[58:59], v[148:149]
	v_pk_mul_f32 v[54:55], v[54:55], v[144:145]
	v_pk_mul_f32 v[64:65], v[64:65], v[154:155]
	v_pk_mul_f32 v[60:61], v[60:61], v[150:151]
	v_pk_mul_f32 v[56:57], v[56:57], v[146:147]
	v_pk_mul_f32 v[52:53], v[52:53], v[142:143]
	v_pk_mul_f32 v[50:51], v[50:51], v[140:141]
	v_pk_mul_f32 v[46:47], v[46:47], v[152:153]
	v_pk_mul_f32 v[42:43], v[42:43], v[148:149]
	v_pk_mul_f32 v[38:39], v[38:39], v[144:145]
	v_pk_mul_f32 v[48:49], v[48:49], v[154:155]
	v_pk_mul_f32 v[44:45], v[44:45], v[150:151]
	v_pk_mul_f32 v[40:41], v[40:41], v[146:147]
	v_pk_mul_f32 v[36:37], v[36:37], v[142:143]
	v_pk_mul_f32 v[34:35], v[34:35], v[140:141]
	v_pk_mul_f32 v[30:31], v[30:31], v[152:153]
	v_pk_mul_f32 v[26:27], v[26:27], v[148:149]
	v_pk_mul_f32 v[22:23], v[22:23], v[144:145]
	v_pk_mul_f32 v[32:33], v[32:33], v[154:155]
	v_pk_mul_f32 v[28:29], v[28:29], v[150:151]
	v_pk_mul_f32 v[24:25], v[24:25], v[146:147]
	v_pk_mul_f32 v[20:21], v[20:21], v[142:143]
	v_pk_mul_f32 v[18:19], v[18:19], v[140:141]
	v_pk_mul_f32 v[14:15], v[14:15], v[152:153]
	v_pk_mul_f32 v[10:11], v[10:11], v[148:149]
	v_pk_mul_f32 v[6:7], v[6:7], v[144:145]
	v_pk_mul_f32 v[16:17], v[16:17], v[154:155]
	v_pk_mul_f32 v[12:13], v[12:13], v[150:151]
	v_pk_mul_f32 v[8:9], v[8:9], v[146:147]
	v_pk_mul_f32 v[4:5], v[4:5], v[142:143]
	v_pk_mul_f32 v[2:3], v[2:3], v[140:141]

; #define LAS __attribute__((address_space(3)))
; DI int v_rd_base(int lane) { return ((lane & 3) << 3) | (((lane >> 2) & 3) << 6) | (((lane >> 4) & 1) << 5) | (((lane >> 5) & 1) << 8); }
; #define PV_RD(D0, L0, H0, L1, H1) L0 = TRB(v_rd_off(D0, 0, 0)); H0 = TRB(v_rd_off(D0, 0, 1)); L1 = TRB(v_rd_off(D0, 1, 0)); H1 = TRB(v_rd_off(D0, 1, 1))
; #define PV_MM(D0, L0, H0, L1, H1) o[D0] = MFMA32(pa0, PK8(L0, H0), o[D0]); o[D0] = MFMA32(pa1, PK8(L1, H1), o[D0])
; #define SB() __builtin_amdgcn_sched_barrier(0)
; DI void phase_attn(int wid0, const Params& p, int L, unsigned char* lds, bool dry) {
;     ...
;                 LAS unsigned char* vbp = ldsl + 65536 + (t & 1) * 32768 + 16384 + v_rd_base(lane);
;                 __builtin_amdgcn_s_setprio(1);
;     ...
;                 {
;                     s16x4 a0, a1, a2, a3, b0_, b1_, b2_, b3_;
;                     PV_RD(0, a0, a1, a2, a3); SB();
;                     PV_RD(1, b0_, b1_, b2_, b3_); SB(); PV_MM(0, a0, a1, a2, a3); SB();
;                     PV_RD(2, a0, a1, a2, a3); SB(); PV_MM(1, b0_, b1_, b2_, b3_); SB();
;                     PV_RD(3, b0_, b1_, b2_, b3_); SB(); PV_MM(2, a0, a1, a2, a3); SB();
;                     PV_RD(4, a0, a1, a2, a3); SB(); PV_MM(3, b0_, b1_, b2_, b3_); SB();
;                     PV_RD(5, b0_, b1_, b2_, b3_); SB(); PV_MM(4, a0, a1, a2, a3); SB();
;                     PV_RD(6, a0, a1, a2, a3); SB(); PV_MM(5, b0_, b1_, b2_, b3_); SB();
;                     PV_RD(7, b0_, b1_, b2_, b3_); SB(); PV_MM(6, a0, a1, a2, a3); SB();
;                     PV_MM(7, b0_, b1_, b2_, b3_); SB();
;                 }
;     ...
;                 __builtin_amdgcn_s_setprio(0);
.Lattn_pvplain1:
	v_add_u32_e32 v0, s101, v212
	s_setprio 1
	ds_read_b64_tr_b16 v[140:141], v0 offset:16384
	ds_read_b64_tr_b16 v[142:143], v0 offset:20480
	ds_read_b64_tr_b16 v[144:145], v0 offset:24576
	ds_read_b64_tr_b16 v[146:147], v0 offset:28672
	ds_read_b64_tr_b16 v[148:149], v0 offset:16896
	ds_read_b64_tr_b16 v[150:151], v0 offset:20992
	ds_read_b64_tr_b16 v[152:153], v0 offset:25088
	ds_read_b64_tr_b16 v[154:155], v0 offset:29184
	s_waitcnt lgkmcnt(6)
	v_mfma_f32_32x32x16_bf16 v[114:129], v[156:159], v[140:143], v[114:129]
	s_waitcnt lgkmcnt(4)
	v_mfma_f32_32x32x16_bf16 v[114:129], v[160:163], v[144:147], v[114:129]
	ds_read_b64_tr_b16 v[140:141], v0 offset:17408
	ds_read_b64_tr_b16 v[142:143], v0 offset:21504
	ds_read_b64_tr_b16 v[144:145], v0 offset:25600
	ds_read_b64_tr_b16 v[146:147], v0 offset:29696
	s_waitcnt lgkmcnt(6)
	v_mfma_f32_32x32x16_bf16 v[98:113], v[156:159], v[148:151], v[98:113]
	s_waitcnt lgkmcnt(4)
	v_mfma_f32_32x32x16_bf16 v[98:113], v[160:163], v[152:155], v[98:113]
	ds_read_b64_tr_b16 v[148:149], v0 offset:17920
	ds_read_b64_tr_b16 v[150:151], v0 offset:22016
	ds_read_b64_tr_b16 v[152:153], v0 offset:26112
	ds_read_b64_tr_b16 v[154:155], v0 offset:30208
	s_waitcnt lgkmcnt(6)
	v_mfma_f32_32x32x16_bf16 v[82:97], v[156:159], v[140:143], v[82:97]
	s_waitcnt lgkmcnt(4)
	v_mfma_f32_32x32x16_bf16 v[82:97], v[160:163], v[144:147], v[82:97]
	ds_read_b64_tr_b16 v[140:141], v0 offset:18432
	ds_read_b64_tr_b16 v[142:143], v0 offset:22528
	ds_read_b64_tr_b16 v[144:145], v0 offset:26624
	ds_read_b64_tr_b16 v[146:147], v0 offset:30720
	s_waitcnt lgkmcnt(6)
	v_mfma_f32_32x32x16_bf16 v[66:81], v[156:159], v[148:151], v[66:81]
	s_waitcnt lgkmcnt(4)
	v_mfma_f32_32x32x16_bf16 v[66:81], v[160:163], v[152:155], v[66:81]
	ds_read_b64_tr_b16 v[148:149], v0 offset:18944
	ds_read_b64_tr_b16 v[150:151], v0 offset:23040
	ds_read_b64_tr_b16 v[152:153], v0 offset:27136
	ds_read_b64_tr_b16 v[154:155], v0 offset:31232
	s_waitcnt lgkmcnt(6)
	v_mfma_f32_32x32x16_bf16 v[50:65], v[156:159], v[140:143], v[50:65]
	s_waitcnt lgkmcnt(4)
	v_mfma_f32_32x32x16_bf16 v[50:65], v[160:163], v[144:147], v[50:65]
	ds_read_b64_tr_b16 v[140:141], v0 offset:19456
	ds_read_b64_tr_b16 v[142:143], v0 offset:23552
	ds_read_b64_tr_b16 v[144:145], v0 offset:27648
	ds_read_b64_tr_b16 v[146:147], v0 offset:31744
	s_waitcnt lgkmcnt(6)
	v_mfma_f32_32x32x16_bf16 v[34:49], v[156:159], v[148:151], v[34:49]
	s_waitcnt lgkmcnt(4)
	v_mfma_f32_32x32x16_bf16 v[34:49], v[160:163], v[152:155], v[34:49]
	ds_read_b64_tr_b16 v[148:149], v0 offset:19968
	ds_read_b64_tr_b16 v[150:151], v0 offset:24064
	ds_read_b64_tr_b16 v[152:153], v0 offset:28160
	ds_read_b64_tr_b16 v[154:155], v0 offset:32256
	s_waitcnt lgkmcnt(6)
	v_mfma_f32_32x32x16_bf16 v[18:33], v[156:159], v[140:143], v[18:33]
	s_waitcnt lgkmcnt(4)
	v_mfma_f32_32x32x16_bf16 v[18:33], v[160:163], v[144:147], v[18:33]
	s_waitcnt lgkmcnt(2)
	v_mfma_f32_32x32x16_bf16 v[2:17], v[156:159], v[148:151], v[2:17]
	s_waitcnt lgkmcnt(0)
	v_mfma_f32_32x32x16_bf16 v[2:17], v[160:163], v[152:155], v[2:17]
	s_setprio 0
	s_andn2_b32 s100, s100, 0x100
	s_bitcmp1_b32 s100, 9
	s_cbranch_scc1 .LBB0_113

; DI void phase_attn(int wid0, const Params& p, int L, unsigned char* lds, bool dry) {
;     ...
;                 __builtin_amdgcn_s_setprio(0);
;             }
;         }
;         finalize_attn(p, lds, o, l_reg, lane_k, wid, meta, qrow0, hh, di, lambda_init, dry);
.Lattn_exit0:
	s_bitcmp1_b32 s100, 8
	s_cbranch_scc0 .LBB0_113
	s_or_b32 s100, s100, 0x200
	s_branch .Lattn_pvplain1
.Lattn_exit1:
	s_bitcmp1_b32 s100, 8
	s_cbranch_scc0 .LBB0_113
	s_or_b32 s100, s100, 0x200
	s_branch .Lattn_pvplain0

; DI void phase_attn(int wid0, const Params& p, int L, unsigned char* lds, bool dry) {
;     ...
;         __syncthreads();
;     }
; }
.LBB0_128:
	v_mov_b64_e32 v[164:165], 0x400
	v_mov_b64_e32 v[166:167], 0x3ff
	v_mov_b64_e32 v[168:169], 0xc00
	v_mov_b64_e32 v[170:171], 0xbff
	v_mov_b64_e32 v[172:173], 0x200
	v_mov_b64_e32 v[174:175], 0x1ff
	v_mov_b32_e32 v232, v1
	v_mov_b32_e32 v233, v1
	v_mov_b32_e32 v234, v1
	v_mov_b32_e32 v235, v1
	v_mov_b32_e32 v188, 0x41b17218
	s_mov_b64 s[4:5], 0
	s_movk_i32 s40, 0x7fff
	v_readlane_b32 s41, v245, 48
